# static s_setprio 3 (was 1) at entry for one block of each co-resident pair
# speedup vs baseline: 1.0174x; 1.0013x over previous
_Z14fwd_megakernel6Params:
	s_load_dwordx16 s[36:51], s[0:1], 0x80
	s_load_dword s3, s[0:1], 0xc0
	s_add_u32 s4, s0, 0xc0
	s_addc_u32 s5, s1, 0
	s_getreg_b32 s6, hwreg(HW_REG_XCC_ID, 0, 4)
	s_waitcnt lgkmcnt(0)
	s_lshr_b32 s7, s2, 5
	s_xor_b32 s7, s7, s2
	s_bitcmp1_b32 s7, 3
	s_cbranch_scc0 .Lmy_prio_skip
	s_setprio 3
